# O9S + P3 tail (beta/decay logit columns) rewritten as a fully unrolled 32-step loop with 8 steps of loads in flight
# baseline (speedup 1.0000x reference)
.LBB0_443:
	v_add_co_u32_e32 v22, vcc, 0x2b500000, v16
	s_nop 1
	v_addc_co_u32_e32 v23, vcc, 0, v17, vcc
	v_add_co_u32_e32 v24, vcc, 0x2b520000, v16
	s_nop 1
	v_addc_co_u32_e32 v25, vcc, 0, v17, vcc
	global_load_dwordx4 v[28:31], v[20:21], off offset:-512
	global_load_dwordx4 v[32:35], v[22:23], off
	global_load_dwordx4 v[36:39], v[24:25], off
	global_load_dwordx4 v[40:43], v[20:21], off offset:-448
	global_load_dwordx4 v[44:47], v[22:23], off offset:64
	global_load_dwordx4 v[48:51], v[24:25], off offset:64
	global_load_dwordx4 v[52:55], v[20:21], off offset:-384
	global_load_dwordx4 v[56:59], v[22:23], off offset:128
	global_load_dwordx4 v[60:63], v[24:25], off offset:128
	global_load_dwordx4 v[64:67], v[20:21], off offset:-320
	global_load_dwordx4 v[68:71], v[22:23], off offset:192
	global_load_dwordx4 v[72:75], v[24:25], off offset:192
	global_load_dwordx4 v[76:79], v[20:21], off offset:-256
	global_load_dwordx4 v[80:83], v[22:23], off offset:256
	global_load_dwordx4 v[84:87], v[24:25], off offset:256
	global_load_dwordx4 v[88:91], v[20:21], off offset:-192
	global_load_dwordx4 v[92:95], v[22:23], off offset:320
	global_load_dwordx4 v[96:99], v[24:25], off offset:320
	global_load_dwordx4 v[100:103], v[20:21], off offset:-128
	global_load_dwordx4 v[104:107], v[22:23], off offset:384
	global_load_dwordx4 v[108:111], v[24:25], off offset:384
	global_load_dwordx4 v[112:115], v[20:21], off offset:-64
	global_load_dwordx4 v[116:119], v[22:23], off offset:448
	global_load_dwordx4 v[120:123], v[24:25], off offset:448
	s_waitcnt vmcnt(21)
	v_mfma_f32_16x16x32_bf16 v[4:7], v[28:31], v[32:35], v[4:7]
	v_mfma_f32_16x16x32_bf16 v[8:11], v[28:31], v[36:39], v[8:11]
	global_load_dwordx4 v[28:31], v[20:21], off
	global_load_dwordx4 v[32:35], v[22:23], off offset:512
	global_load_dwordx4 v[36:39], v[24:25], off offset:512
	s_waitcnt vmcnt(21)
	v_mfma_f32_16x16x32_bf16 v[4:7], v[40:43], v[44:47], v[4:7]
	v_mfma_f32_16x16x32_bf16 v[8:11], v[40:43], v[48:51], v[8:11]
	global_load_dwordx4 v[40:43], v[20:21], off offset:64
	global_load_dwordx4 v[44:47], v[22:23], off offset:576
	global_load_dwordx4 v[48:51], v[24:25], off offset:576
	s_waitcnt vmcnt(21)
	v_mfma_f32_16x16x32_bf16 v[4:7], v[52:55], v[56:59], v[4:7]
	v_mfma_f32_16x16x32_bf16 v[8:11], v[52:55], v[60:63], v[8:11]
	global_load_dwordx4 v[52:55], v[20:21], off offset:128
	global_load_dwordx4 v[56:59], v[22:23], off offset:640
	global_load_dwordx4 v[60:63], v[24:25], off offset:640
	s_waitcnt vmcnt(21)
	v_mfma_f32_16x16x32_bf16 v[4:7], v[64:67], v[68:71], v[4:7]
	v_mfma_f32_16x16x32_bf16 v[8:11], v[64:67], v[72:75], v[8:11]
	global_load_dwordx4 v[64:67], v[20:21], off offset:192
	global_load_dwordx4 v[68:71], v[22:23], off offset:704
	global_load_dwordx4 v[72:75], v[24:25], off offset:704
	s_waitcnt vmcnt(21)
	v_mfma_f32_16x16x32_bf16 v[4:7], v[76:79], v[80:83], v[4:7]
	v_mfma_f32_16x16x32_bf16 v[8:11], v[76:79], v[84:87], v[8:11]
	global_load_dwordx4 v[76:79], v[20:21], off offset:256
	global_load_dwordx4 v[80:83], v[22:23], off offset:768
	global_load_dwordx4 v[84:87], v[24:25], off offset:768
	s_waitcnt vmcnt(21)
	v_mfma_f32_16x16x32_bf16 v[4:7], v[88:91], v[92:95], v[4:7]
	v_mfma_f32_16x16x32_bf16 v[8:11], v[88:91], v[96:99], v[8:11]
	global_load_dwordx4 v[88:91], v[20:21], off offset:320
	global_load_dwordx4 v[92:95], v[22:23], off offset:832
	global_load_dwordx4 v[96:99], v[24:25], off offset:832
	s_waitcnt vmcnt(21)
	v_mfma_f32_16x16x32_bf16 v[4:7], v[100:103], v[104:107], v[4:7]
	v_mfma_f32_16x16x32_bf16 v[8:11], v[100:103], v[108:111], v[8:11]
	global_load_dwordx4 v[100:103], v[20:21], off offset:384
	global_load_dwordx4 v[104:107], v[22:23], off offset:896
	global_load_dwordx4 v[108:111], v[24:25], off offset:896
	s_waitcnt vmcnt(21)
	v_mfma_f32_16x16x32_bf16 v[4:7], v[112:115], v[116:119], v[4:7]
	v_mfma_f32_16x16x32_bf16 v[8:11], v[112:115], v[120:123], v[8:11]
	global_load_dwordx4 v[112:115], v[20:21], off offset:448
	global_load_dwordx4 v[116:119], v[22:23], off offset:960
	global_load_dwordx4 v[120:123], v[24:25], off offset:960
	s_waitcnt vmcnt(21)
	v_mfma_f32_16x16x32_bf16 v[4:7], v[28:31], v[32:35], v[4:7]
	v_mfma_f32_16x16x32_bf16 v[8:11], v[28:31], v[36:39], v[8:11]
	global_load_dwordx4 v[28:31], v[20:21], off offset:512
	global_load_dwordx4 v[32:35], v[22:23], off offset:1024
	global_load_dwordx4 v[36:39], v[24:25], off offset:1024
	s_waitcnt vmcnt(21)
	v_mfma_f32_16x16x32_bf16 v[4:7], v[40:43], v[44:47], v[4:7]
	v_mfma_f32_16x16x32_bf16 v[8:11], v[40:43], v[48:51], v[8:11]
	global_load_dwordx4 v[40:43], v[20:21], off offset:576
	global_load_dwordx4 v[44:47], v[22:23], off offset:1088
	global_load_dwordx4 v[48:51], v[24:25], off offset:1088
	s_waitcnt vmcnt(21)
	v_mfma_f32_16x16x32_bf16 v[4:7], v[52:55], v[56:59], v[4:7]
	v_mfma_f32_16x16x32_bf16 v[8:11], v[52:55], v[60:63], v[8:11]
	global_load_dwordx4 v[52:55], v[20:21], off offset:640
	global_load_dwordx4 v[56:59], v[22:23], off offset:1152
	global_load_dwordx4 v[60:63], v[24:25], off offset:1152
	s_waitcnt vmcnt(21)
	v_mfma_f32_16x16x32_bf16 v[4:7], v[64:67], v[68:71], v[4:7]
	v_mfma_f32_16x16x32_bf16 v[8:11], v[64:67], v[72:75], v[8:11]
	global_load_dwordx4 v[64:67], v[20:21], off offset:704
	global_load_dwordx4 v[68:71], v[22:23], off offset:1216
	global_load_dwordx4 v[72:75], v[24:25], off offset:1216
	s_waitcnt vmcnt(21)
	v_mfma_f32_16x16x32_bf16 v[4:7], v[76:79], v[80:83], v[4:7]
	v_mfma_f32_16x16x32_bf16 v[8:11], v[76:79], v[84:87], v[8:11]
	global_load_dwordx4 v[76:79], v[20:21], off offset:768
	global_load_dwordx4 v[80:83], v[22:23], off offset:1280
	global_load_dwordx4 v[84:87], v[24:25], off offset:1280
	s_waitcnt vmcnt(21)
	v_mfma_f32_16x16x32_bf16 v[4:7], v[88:91], v[92:95], v[4:7]
	v_mfma_f32_16x16x32_bf16 v[8:11], v[88:91], v[96:99], v[8:11]
	global_load_dwordx4 v[88:91], v[20:21], off offset:832
	global_load_dwordx4 v[92:95], v[22:23], off offset:1344
	global_load_dwordx4 v[96:99], v[24:25], off offset:1344
	s_waitcnt vmcnt(21)
	v_mfma_f32_16x16x32_bf16 v[4:7], v[100:103], v[104:107], v[4:7]
	v_mfma_f32_16x16x32_bf16 v[8:11], v[100:103], v[108:111], v[8:11]
	global_load_dwordx4 v[100:103], v[20:21], off offset:896
	global_load_dwordx4 v[104:107], v[22:23], off offset:1408
	global_load_dwordx4 v[108:111], v[24:25], off offset:1408
	s_waitcnt vmcnt(21)
	v_mfma_f32_16x16x32_bf16 v[4:7], v[112:115], v[116:119], v[4:7]
	v_mfma_f32_16x16x32_bf16 v[8:11], v[112:115], v[120:123], v[8:11]
	global_load_dwordx4 v[112:115], v[20:21], off offset:960
	global_load_dwordx4 v[116:119], v[22:23], off offset:1472
	global_load_dwordx4 v[120:123], v[24:25], off offset:1472
	s_waitcnt vmcnt(21)
	v_mfma_f32_16x16x32_bf16 v[4:7], v[28:31], v[32:35], v[4:7]
	v_mfma_f32_16x16x32_bf16 v[8:11], v[28:31], v[36:39], v[8:11]
	global_load_dwordx4 v[28:31], v[20:21], off offset:1024
	global_load_dwordx4 v[32:35], v[22:23], off offset:1536
	global_load_dwordx4 v[36:39], v[24:25], off offset:1536
	s_waitcnt vmcnt(21)
	v_mfma_f32_16x16x32_bf16 v[4:7], v[40:43], v[44:47], v[4:7]
	v_mfma_f32_16x16x32_bf16 v[8:11], v[40:43], v[48:51], v[8:11]
	global_load_dwordx4 v[40:43], v[20:21], off offset:1088
	global_load_dwordx4 v[44:47], v[22:23], off offset:1600
	global_load_dwordx4 v[48:51], v[24:25], off offset:1600
	s_waitcnt vmcnt(21)
	v_mfma_f32_16x16x32_bf16 v[4:7], v[52:55], v[56:59], v[4:7]
	v_mfma_f32_16x16x32_bf16 v[8:11], v[52:55], v[60:63], v[8:11]
	global_load_dwordx4 v[52:55], v[20:21], off offset:1152
	global_load_dwordx4 v[56:59], v[22:23], off offset:1664
	global_load_dwordx4 v[60:63], v[24:25], off offset:1664
	s_waitcnt vmcnt(21)
	v_mfma_f32_16x16x32_bf16 v[4:7], v[64:67], v[68:71], v[4:7]
	v_mfma_f32_16x16x32_bf16 v[8:11], v[64:67], v[72:75], v[8:11]
	global_load_dwordx4 v[64:67], v[20:21], off offset:1216
	global_load_dwordx4 v[68:71], v[22:23], off offset:1728
	global_load_dwordx4 v[72:75], v[24:25], off offset:1728
	s_waitcnt vmcnt(21)
	v_mfma_f32_16x16x32_bf16 v[4:7], v[76:79], v[80:83], v[4:7]
	v_mfma_f32_16x16x32_bf16 v[8:11], v[76:79], v[84:87], v[8:11]
	global_load_dwordx4 v[76:79], v[20:21], off offset:1280
	global_load_dwordx4 v[80:83], v[22:23], off offset:1792
	global_load_dwordx4 v[84:87], v[24:25], off offset:1792
	s_waitcnt vmcnt(21)
	v_mfma_f32_16x16x32_bf16 v[4:7], v[88:91], v[92:95], v[4:7]
	v_mfma_f32_16x16x32_bf16 v[8:11], v[88:91], v[96:99], v[8:11]
	global_load_dwordx4 v[88:91], v[20:21], off offset:1344
	global_load_dwordx4 v[92:95], v[22:23], off offset:1856
	global_load_dwordx4 v[96:99], v[24:25], off offset:1856
	s_waitcnt vmcnt(21)
	v_mfma_f32_16x16x32_bf16 v[4:7], v[100:103], v[104:107], v[4:7]
	v_mfma_f32_16x16x32_bf16 v[8:11], v[100:103], v[108:111], v[8:11]
	global_load_dwordx4 v[100:103], v[20:21], off offset:1408
	global_load_dwordx4 v[104:107], v[22:23], off offset:1920
	global_load_dwordx4 v[108:111], v[24:25], off offset:1920
	s_waitcnt vmcnt(21)
	v_mfma_f32_16x16x32_bf16 v[4:7], v[112:115], v[116:119], v[4:7]
	v_mfma_f32_16x16x32_bf16 v[8:11], v[112:115], v[120:123], v[8:11]
	global_load_dwordx4 v[112:115], v[20:21], off offset:1472
	global_load_dwordx4 v[116:119], v[22:23], off offset:1984
	global_load_dwordx4 v[120:123], v[24:25], off offset:1984
	s_waitcnt vmcnt(21)
	v_mfma_f32_16x16x32_bf16 v[4:7], v[28:31], v[32:35], v[4:7]
	v_mfma_f32_16x16x32_bf16 v[8:11], v[28:31], v[36:39], v[8:11]
	s_waitcnt vmcnt(18)
	v_mfma_f32_16x16x32_bf16 v[4:7], v[40:43], v[44:47], v[4:7]
	v_mfma_f32_16x16x32_bf16 v[8:11], v[40:43], v[48:51], v[8:11]
	s_waitcnt vmcnt(15)
	v_mfma_f32_16x16x32_bf16 v[4:7], v[52:55], v[56:59], v[4:7]
	v_mfma_f32_16x16x32_bf16 v[8:11], v[52:55], v[60:63], v[8:11]
	s_waitcnt vmcnt(12)
	v_mfma_f32_16x16x32_bf16 v[4:7], v[64:67], v[68:71], v[4:7]
	v_mfma_f32_16x16x32_bf16 v[8:11], v[64:67], v[72:75], v[8:11]
	s_waitcnt vmcnt(9)
	v_mfma_f32_16x16x32_bf16 v[4:7], v[76:79], v[80:83], v[4:7]
	v_mfma_f32_16x16x32_bf16 v[8:11], v[76:79], v[84:87], v[8:11]
	s_waitcnt vmcnt(6)
	v_mfma_f32_16x16x32_bf16 v[4:7], v[88:91], v[92:95], v[4:7]
	v_mfma_f32_16x16x32_bf16 v[8:11], v[88:91], v[96:99], v[8:11]
	s_waitcnt vmcnt(3)
	v_mfma_f32_16x16x32_bf16 v[4:7], v[100:103], v[104:107], v[4:7]
	v_mfma_f32_16x16x32_bf16 v[8:11], v[100:103], v[108:111], v[8:11]
	s_waitcnt vmcnt(0)
	v_mfma_f32_16x16x32_bf16 v[4:7], v[112:115], v[116:119], v[4:7]
	v_mfma_f32_16x16x32_bf16 v[8:11], v[112:115], v[120:123], v[8:11]
	s_and_b32 s2, s4, 0x3ffffffc
	v_or_b32_e32 v3, s2, v1
	v_lshlrev_b32_e32 v20, 2, v3
	v_ashrrev_i32_e32 v21, 31, v20
	v_lshlrev_b64 v[20:21], 7, v[20:21]
	s_add_i32 s4, s4, s34
	s_add_i32 s0, s0, s1
	v_lshl_add_u64 v[20:21], v[14:15], 0, v[20:21]
	s_cmpk_lt_i32 s4, 0x800
	global_store_dword v[20:21], v4, off
	global_store_dword v[20:21], v8, off offset:64
	global_store_dword v[20:21], v5, off offset:128
	global_store_dword v[20:21], v9, off offset:192
	global_store_dword v[20:21], v6, off offset:256
	global_store_dword v[20:21], v10, off offset:320
	global_store_dword v[20:21], v7, off offset:384
	global_store_dword v[20:21], v11, off offset:448
	s_cbranch_scc1 .LBB0_442
